# L1 invalidate (buffer_inv sc1) issued right behind the barrier-arrival / queue-pop atomics instead of after the spin, at 3 grid barriers + ticket + 2 ready-queue pops
# speedup vs baseline: 1.0258x; 1.0079x over previous
.LBB0_53:
	s_mov_b64 s[6:7], exec
	v_readlane_b32 s0, v247, 15
	s_lshl_b32 s0, s0, 8
	v_readlane_b32 s4, v247, 13
	v_mbcnt_lo_u32_b32 v1, s6, 0
	v_readlane_b32 s5, v247, 14
	s_add_u32 s4, s4, s0
	v_mbcnt_hi_u32_b32 v1, s7, v1
	s_addc_u32 s5, s5, 0
	v_cmp_eq_u32_e32 vcc, 0, v1
	s_and_saveexec_b64 s[8:9], vcc
	s_cbranch_execz .LBB0_55
	s_bcnt1_i32_b64 s0, s[6:7]
	v_mov_b32_e32 v3, 0x1000
	v_mov_b32_e32 v4, s0
	global_atomic_add v3, v3, v4, s[4:5] offset:1024 sc0
	buffer_inv sc1

.LBB0_68:
	s_or_b64 exec, exec, s[8:9]
	s_waitcnt vmcnt(0)
	s_waitcnt vmcnt(0)

.LBB0_549:
	s_waitcnt vmcnt(0)
	v_readlane_b32 s0, v247, 16
	v_readlane_b32 s1, v247, 17
	v_readlane_b32 s66, v247, 35
	v_readlane_b32 s72, v247, 18
	v_readlane_b32 s50, v247, 53
	s_and_b64 vcc, exec, s[0:1]
	v_readlane_b32 s67, v247, 36
	v_readlane_b32 s73, v247, 19
	v_readlane_b32 s74, v247, 33
	v_readlane_b32 s51, v247, 54
	s_barrier
	s_cbranch_vccz .LBB0_570
	v_mbcnt_lo_u32_b32 v0, -1, 0
	v_mbcnt_hi_u32_b32 v0, -1, v0
	s_nop 0
	v_cmp_eq_u32_e32 vcc, 0, v0
	s_and_saveexec_b64 s[2:3], vcc
	s_cbranch_execz .LBB0_569
	s_mov_b64 s[6:7], exec
	v_mbcnt_lo_u32_b32 v0, s6, 0
	v_mbcnt_hi_u32_b32 v0, s7, v0
	v_cmp_eq_u32_e32 vcc, 0, v0
	s_and_saveexec_b64 s[4:5], vcc
	s_cbranch_execz .LBB0_553
	s_bcnt1_i32_b64 s0, s[6:7]
	v_mov_b32_e32 v1, 0x8000
	v_mov_b32_e32 v2, s0
	global_atomic_add v1, v1, v2, s[66:67] offset:1536 sc0
	buffer_inv sc1

.LBB0_567:
	s_waitcnt vmcnt(0)
	s_waitcnt vmcnt(0)

.LBB0_591:
.LBB0_592:
	s_and_b64 vcc, exec, s[72:73]
	s_barrier
	s_cbranch_vccnz .LBB0_614
	v_mbcnt_lo_u32_b32 v0, -1, 0
	v_mbcnt_hi_u32_b32 v0, -1, v0
	s_nop 0
	v_cmp_eq_u32_e32 vcc, 0, v0
	s_and_saveexec_b64 s[4:5], vcc
	s_cbranch_execz .LBB0_613
	s_mov_b64 s[8:9], exec
	v_mbcnt_lo_u32_b32 v0, s8, 0
	v_mbcnt_hi_u32_b32 v0, s9, v0
	v_cmp_eq_u32_e32 vcc, 0, v0
	s_and_saveexec_b64 s[6:7], vcc
	s_cbranch_execz .LBB0_596
	s_bcnt1_i32_b64 s8, s[8:9]
	v_mov_b32_e32 v1, s8
	global_atomic_add v1, v9, v1, s[2:3] sc0
	buffer_inv sc1

.LBB0_628:
	s_and_b64 vcc, exec, s[72:73]
	s_barrier
	s_cbranch_vccnz .LBB0_650
	v_mbcnt_lo_u32_b32 v0, -1, 0
	v_mbcnt_hi_u32_b32 v0, -1, v0
	s_nop 0
	v_cmp_eq_u32_e32 vcc, 0, v0
	s_and_saveexec_b64 s[16:17], vcc
	s_cbranch_execz .LBB0_649
	s_mov_b64 s[22:23], exec
	v_mbcnt_lo_u32_b32 v0, s22, 0
	v_mbcnt_hi_u32_b32 v0, s23, v0
	v_cmp_eq_u32_e32 vcc, 0, v0
	s_and_saveexec_b64 s[18:19], vcc
	s_cbranch_execz .LBB0_632
	s_bcnt1_i32_b64 s22, s[22:23]
	v_mov_b32_e32 v1, s22
	global_atomic_add v1, v129, v1, s[4:5] sc0
	buffer_inv sc1

.LBB0_647:
	s_or_b64 exec, exec, s[22:23]
	s_waitcnt vmcnt(0)
	s_waitcnt vmcnt(0)

.LBB0_675:
	s_mov_b64 s[8:9], exec
	v_readlane_b32 s0, v247, 15
	s_lshl_b32 s0, s0, 8
	v_readlane_b32 s6, v247, 13
	v_mbcnt_lo_u32_b32 v1, s8, 0
	v_readlane_b32 s7, v247, 14
	s_add_u32 s6, s6, s0
	v_mbcnt_hi_u32_b32 v1, s9, v1
	s_addc_u32 s7, s7, 0
	v_cmp_eq_u32_e32 vcc, 0, v1
	s_and_saveexec_b64 s[10:11], vcc
	s_cbranch_execz .LBB0_677
	s_bcnt1_i32_b64 s0, s[8:9]
	v_mov_b32_e32 v3, 0x1000
	v_mov_b32_e32 v4, s0
	global_atomic_add v3, v3, v4, s[6:7] offset:1024 sc0
	buffer_inv sc1

.LBB0_690:
	s_or_b64 exec, exec, s[10:11]
	s_waitcnt vmcnt(0)
	s_waitcnt vmcnt(0)
